# K=1024 GEMMs: per-row RMS sums preloaded at unit set-up for both the SwiGLU and the input-projection epilogues (no blocking loads after the K-loop)
# baseline (speedup 1.0000x reference)
; __device__ __forceinline__ unsigned cvtpk(float lo, float hi) { f32x2 v = {lo, hi}; bf16x2_t b = __builtin_convertvector(v, bf16x2_t); return __builtin_bit_cast(unsigned, b); }
;     __device__ __forceinline__ void operator()(const pg8::f32x4 (&acc)[2][2][4][2], const pg8::Unit& u, int wr, int wc, int fr, int fq) const {
;     ...
;         } else if (kind == EK_BF16 && PERM) {
; #pragma unroll
;             for (int bj = 0; bj < 2; ++bj) {
;                 const int c = colb + 128 * bj;
;                 if (c < ncols) {
; #pragma unroll
;                     for (int ai = 0; ai < 2; ++ai)
; #pragma unroll
;                         for (int m = 0; m < 4; ++m) {
;                             pg8::f32x4 v0 = acc[ai][bj][m][0], v1 = acc[ai][bj][m][1];
;                             if (flags & 4) { const float rs = __builtin_amdgcn_rsqf(fin[rowb + 128 * ai + 16 * m] * (1.0f / DM) + EPS); v0 = v0 * rs; v1 = v1 * rs; }
;                             *(u32x4*)(o0 + (size_t)(rowb + 128 * ai + 16 * m) * ldc + c) = (u32x4){cvtpk(v0[0], v0[1]), cvtpk(v0[2], v0[3]), cvtpk(v1[0], v1[1]), cvtpk(v1[2], v1[3])};
.LBB0_1143:
	v_mov_b32_e32 v64, v192
	v_mov_b32_e32 v65, v193
	v_mov_b32_e32 v66, v194
	v_mov_b32_e32 v67, v195
	v_mov_b32_e32 v68, v196
	v_mov_b32_e32 v69, v197
	v_mov_b32_e32 v70, v198
	v_mov_b32_e32 v71, v199
	v_mov_b32_e32 v136, v200
	v_mov_b32_e32 v137, v201
	v_mov_b32_e32 v138, v202
	v_mov_b32_e32 v139, v203
	v_lshl_add_u32 v228, s8, 8, v252
	s_mov_b64 s[8:9], -1
	v_readfirstlane_b32 s47, v192
	s_cmp_lt_i32 s47, 1
	s_cbranch_scc1 .LBB0_1235
	v_lshl_or_b32 v230, s54, 8, v248
	s_cmp_lt_i32 s47, 2
	s_cbranch_scc1 .LBB0_1184
	s_cmp_eq_u32 s47, 2
	s_cbranch_scc0 .LBB0_1183
	v_and_b32_e32 v64, 4, v67
	v_cmp_ne_u32_e64 s[8:9], 0, v64
	v_cmp_lt_i32_e32 vcc, v230, v66
	s_nop 0
	v_cndmask_b32_e64 v64, 0, 1, s[8:9]
	v_cmp_ne_u32_e64 s[8:9], 1, v64
	s_and_saveexec_b64 s[10:11], vcc
	s_cbranch_execz .LBB0_1164
	v_ashrrev_i32_e32 v229, 31, v228
	v_mov_b64_e32 v[142:143], v[134:135]
	v_mov_b64_e32 v[146:147], v[130:131]
	s_and_b64 vcc, exec, s[8:9]
	v_lshl_add_u64 v[150:151], v[228:229], 2, v[136:137]
	v_mov_b64_e32 v[140:141], v[132:133]
	v_mov_b64_e32 v[144:145], v[128:129]
	s_cbranch_vccnz .Lepi_pre_skip_1
	v_mov_b32_e32 v152, v204
	v_mov_b32_e32 v153, v205
	v_mov_b32_e32 v154, v206
	v_mov_b32_e32 v155, v207
	v_mov_b32_e32 v156, v208
	v_mov_b32_e32 v157, v209
	v_mov_b32_e32 v158, v210
	v_mov_b32_e32 v159, v211

; __device__ __forceinline__ unsigned cvtpk(float lo, float hi) { f32x2 v = {lo, hi}; bf16x2_t b = __builtin_convertvector(v, bf16x2_t); return __builtin_bit_cast(unsigned, b); }
;     __device__ __forceinline__ void operator()(const pg8::f32x4 (&acc)[2][2][4][2], const pg8::Unit& u, int wr, int wc, int fr, int fq) const {
;     ...
;             for (int bj = 0; bj < 2; ++bj) {
;                 const int c = colb + 128 * bj;
;                 if (c < ncols) {
; #pragma unroll
;                     for (int ai = 0; ai < 2; ++ai)
; #pragma unroll
;                         for (int m = 0; m < 4; ++m) {
;                             pg8::f32x4 v0 = acc[ai][bj][m][0], v1 = acc[ai][bj][m][1];
;                             if (flags & 4) { const float rs = __builtin_amdgcn_rsqf(fin[rowb + 128 * ai + 16 * m] * (1.0f / DM) + EPS); v0 = v0 * rs; v1 = v1 * rs; }
;                             *(u32x4*)(o0 + (size_t)(rowb + 128 * ai + 16 * m) * ldc + c) = (u32x4){cvtpk(v0[0], v0[1]), cvtpk(v0[2], v0[3]), cvtpk(v1[0], v1[1]), cvtpk(v1[2], v1[3])};
.LBB0_1164:
	s_or_b64 exec, exec, s[10:11]
	v_or_b32_e32 v64, 0x80, v230
	v_cmp_lt_i32_e32 vcc, v64, v66
	s_and_saveexec_b64 s[10:11], vcc
	s_cbranch_execz .LBB0_1182
	v_ashrrev_i32_e32 v229, 31, v228
	v_mov_b64_e32 v[142:143], v[126:127]
	v_mov_b64_e32 v[146:147], v[122:123]
	s_and_b64 vcc, exec, s[8:9]
	v_lshl_add_u64 v[150:151], v[228:229], 2, v[136:137]
	v_mov_b64_e32 v[140:141], v[124:125]
	v_mov_b64_e32 v[144:145], v[120:121]
	s_cbranch_vccnz .Lepi_pre_skip_2
	v_mov_b32_e32 v152, v204
	v_mov_b32_e32 v153, v205
	v_mov_b32_e32 v154, v206
	v_mov_b32_e32 v155, v207
	v_mov_b32_e32 v156, v208
	v_mov_b32_e32 v157, v209
	v_mov_b32_e32 v158, v210
	v_mov_b32_e32 v159, v211
